# QKV kv tiles (K=128 gemm_tile_glds, both layers): stage-1 LDS-DMA loads and their address setup hoisted behind stage-0 issue; first wait relaxed to vmcnt(8)
# speedup vs baseline: 1.0016x; 1.0016x over previous
.LBB0_544:
	s_and_b64 vcc, exec, s[4:5]
	s_cbranch_vccz .LBB0_611
	s_add_i32 s4, s83, 0xfe68
	v_mov_b32_e32 v116, v164
	s_bfe_u32 s2, s4, 0xe0002
	s_lshl_b32 s1, s2, 7
	v_bfe_u32 v4, v116, 3, 5
	v_xor_b32_e32 v5, v4, v116
	s_and_b32 s0, s83, 3
	v_or_b32_e32 v6, s1, v4
	v_mov_b64_e32 v[0:1], s[18:19]
	v_lshlrev_b32_e32 v5, 4, v5
	v_mad_u64_u32 v[0:1], s[40:41], v6, s80, v[0:1]
	v_and_b32_e32 v64, 0x70, v5
	s_lshl_b32 s5, s0, 15
	v_lshl_add_u64 v[92:93], v[0:1], 0, v[64:65]
	v_lshl_or_b32 v0, v4, 8, s5
	v_mov_b32_e32 v1, v65
	v_and_b32_e32 v3, 0xff, v116
	v_lshl_add_u64 v[0:1], s[28:29], 0, v[0:1]
	v_lshl_add_u64 v[94:95], v[0:1], 0, v[64:65]
	v_lshl_add_u32 v64, v3, 4, s23
	v_add_u32_e32 v3, 0x1000, v64
	v_readfirstlane_b32 s5, v64
	s_mov_b32 m0, s5
	v_readfirstlane_b32 s5, v3
	v_add_u32_e32 v3, 0x2000, v64
	global_load_lds_dwordx4 v[92:93], off
	v_lshl_add_u64 v[0:1], v[92:93], 0, s[36:37]
	s_mov_b32 m0, s5
	v_readfirstlane_b32 s5, v3
	v_add_u32_e32 v3, 0x3000, v64
	global_load_lds_dwordx4 v[0:1], off
	v_lshl_add_u64 v[0:1], v[92:93], 0, s[38:39]
	s_mov_b32 m0, s5
	v_readfirstlane_b32 s5, v3
	global_load_lds_dwordx4 v[0:1], off
	v_lshl_add_u64 v[0:1], v[92:93], 0, s[52:53]
	s_mov_b32 m0, s5
	v_add_u32_e32 v3, 0x5000, v64
	global_load_lds_dwordx4 v[0:1], off
	v_add_u32_e32 v0, 0x4000, v64
	s_mov_b64 s[40:41], 0x2000
	v_readfirstlane_b32 s5, v0
	s_mov_b32 m0, s5
	v_readfirstlane_b32 s5, v3
	v_add_u32_e32 v3, 0x6000, v64
	global_load_lds_dwordx4 v[94:95], off
	v_lshl_add_u64 v[0:1], v[94:95], 0, s[40:41]
	s_mov_b32 m0, s5
	v_readfirstlane_b32 s5, v3
	v_add_u32_e32 v3, 0x7000, v64
	global_load_lds_dwordx4 v[0:1], off
	v_lshl_add_u64 v[0:1], v[94:95], 0, s[54:55]
	s_mov_b32 m0, s5
	s_mov_b64 s[40:41], 0x6000
	v_readfirstlane_b32 s5, v3
	v_lshrrev_b32_e32 v2, 4, v116
	s_waitcnt vmcnt(0)
	v_and_b32_e32 v66, 15, v116
	global_load_lds_dwordx4 v[0:1], off
	v_lshl_add_u64 v[0:1], v[94:95], 0, s[40:41]
	s_mov_b32 m0, s5
	v_and_b32_e32 v72, 7, v116
	v_bfe_u32 v117, v116, 6, 1
	global_load_lds_dwordx4 v[0:1], off
	v_add_u32_e32 v110, 0x8000, v64
	v_add_u32_e32 v111, 0xf000, v64
	v_add_u32_e32 v113, 0xe000, v64
	v_add_u32_e32 v114, 0xd000, v64
	v_add_u32_e32 v115, 0xc000, v64
	v_add_u32_e32 v121, 0xb000, v64
	v_add_u32_e32 v122, 0xa000, v64
	v_add_u32_e32 v64, 0x9000, v64
	v_readfirstlane_b32 s5, v110
	s_mov_b32 m0, s5
	v_readfirstlane_b32 s5, v64
	v_lshl_add_u64 v[106:107], v[92:93], 0, s[64:65]
	s_mov_b64 s[40:41], 0x6080
	v_lshl_add_u64 v[104:105], v[92:93], 0, s[62:63]
	v_lshl_add_u64 v[96:97], v[94:95], 0, s[40:41]
	s_mov_b64 s[40:41], 0x2080
	v_lshl_add_u64 v[102:103], v[92:93], 0, s[60:61]
	v_lshl_add_u64 v[98:99], v[94:95], 0, s[56:57]
	v_lshl_add_u64 v[100:101], v[94:95], 0, s[40:41]
	v_lshl_add_u64 v[94:95], v[94:95], 0, s[58:59]
	v_lshl_add_u64 v[0:1], v[92:93], 0, s[58:59]
	global_load_lds_dwordx4 v[0:1], off
	s_mov_b32 m0, s5
	v_readfirstlane_b32 s5, v122
	global_load_lds_dwordx4 v[106:107], off
	s_mov_b32 m0, s5
	v_readfirstlane_b32 s5, v121
	global_load_lds_dwordx4 v[104:105], off
	s_mov_b32 m0, s5
	v_readfirstlane_b32 s5, v115
	global_load_lds_dwordx4 v[102:103], off
	s_mov_b32 m0, s5
	v_readfirstlane_b32 s5, v114
	global_load_lds_dwordx4 v[94:95], off
	s_mov_b32 m0, s5
	v_readfirstlane_b32 s5, v113
	global_load_lds_dwordx4 v[100:101], off
	s_mov_b32 m0, s5
	v_readfirstlane_b32 s5, v111
	global_load_lds_dwordx4 v[98:99], off
	s_mov_b32 m0, s5
	s_nop 0
	global_load_lds_dwordx4 v[96:97], off
	v_bitop3_b32 v0, v2, v72, 3 bitop3:0x6c
	v_lshlrev_b32_e32 v5, 7, v66
	v_bfe_u32 v118, v116, 7, 1
	v_lshl_add_u32 v4, v0, 4, s23
	v_lshl_or_b32 v73, v117, 13, v5
	v_add_u32_e32 v108, v4, v73
	v_lshl_or_b32 v76, v118, 13, v5
	s_waitcnt vmcnt(8)
	s_waitcnt vmcnt(8) lgkmcnt(0)
	s_barrier
	ds_read_b128 v[0:3], v108 offset:16384
	v_add_u32_e32 v109, v4, v76
	ds_read_b128 v[4:7], v108 offset:18432
	ds_read_b128 v[8:11], v109
	ds_read_b128 v[12:15], v109 offset:2048
	ds_read_b128 v[20:23], v108 offset:20480
	ds_read_b128 v[28:31], v108 offset:22528
	ds_read_b128 v[48:51], v109 offset:4096
	ds_read_b128 v[52:55], v109 offset:6144
	v_bfe_u32 v119, v116, 4, 2
	v_bitop3_b32 v72, v119, v72, 4 bitop3:0x36
	v_lshl_add_u32 v77, v72, 4, s23
	v_add_u32_e32 v112, v77, v73
	s_waitcnt lgkmcnt(5)
	v_mfma_f32_16x16x32_bf16 v[16:19], v[0:3], v[8:11], 0
	ds_read_b128 v[72:75], v112 offset:16384
	v_add_u32_e32 v120, v77, v76
	v_mfma_f32_16x16x32_bf16 v[24:27], v[4:7], v[8:11], 0
	s_waitcnt lgkmcnt(4)
	v_mfma_f32_16x16x32_bf16 v[32:35], v[20:23], v[8:11], 0
	s_waitcnt lgkmcnt(3)
	v_mfma_f32_16x16x32_bf16 v[8:11], v[28:31], v[8:11], 0
	v_mfma_f32_16x16x32_bf16 v[36:39], v[0:3], v[12:15], 0
	v_mfma_f32_16x16x32_bf16 v[40:43], v[4:7], v[12:15], 0
	v_mfma_f32_16x16x32_bf16 v[44:47], v[20:23], v[12:15], 0
	v_mfma_f32_16x16x32_bf16 v[12:15], v[28:31], v[12:15], 0
	s_lshr_b32 s4, s4, 2
	s_waitcnt lgkmcnt(2)
	v_mfma_f32_16x16x32_bf16 v[56:59], v[0:3], v[48:51], 0
	v_mfma_f32_16x16x32_bf16 v[60:63], v[4:7], v[48:51], 0
	v_mfma_f32_16x16x32_bf16 v[68:71], v[20:23], v[48:51], 0
	v_mfma_f32_16x16x32_bf16 v[48:51], v[28:31], v[48:51], 0
	s_waitcnt lgkmcnt(1)
	v_mfma_f32_16x16x32_bf16 v[0:3], v[0:3], v[52:55], 0
	v_mfma_f32_16x16x32_bf16 v[4:7], v[4:7], v[52:55], 0
	v_mfma_f32_16x16x32_bf16 v[20:23], v[20:23], v[52:55], 0
	v_mfma_f32_16x16x32_bf16 v[28:31], v[28:31], v[52:55], 0
	ds_read_b128 v[52:55], v112 offset:18432
	ds_read_b128 v[76:79], v120
	ds_read_b128 v[80:83], v120 offset:2048
	ds_read_b128 v[84:87], v112 offset:20480
	ds_read_b128 v[88:91], v112 offset:22528
	s_waitcnt lgkmcnt(3)
	v_mfma_f32_16x16x32_bf16 v[16:19], v[72:75], v[76:79], v[16:19]
	v_mfma_f32_16x16x32_bf16 v[24:27], v[52:55], v[76:79], v[24:27]
	s_waitcnt lgkmcnt(1)
	v_mfma_f32_16x16x32_bf16 v[32:35], v[84:87], v[76:79], v[32:35]
	s_waitcnt lgkmcnt(0)
	v_mfma_f32_16x16x32_bf16 v[8:11], v[88:91], v[76:79], v[8:11]
	v_mfma_f32_16x16x32_bf16 v[36:39], v[72:75], v[80:83], v[36:39]
	ds_read_b128 v[76:79], v120 offset:4096
	v_mfma_f32_16x16x32_bf16 v[40:43], v[52:55], v[80:83], v[40:43]
	v_mfma_f32_16x16x32_bf16 v[44:47], v[84:87], v[80:83], v[44:47]
	v_mfma_f32_16x16x32_bf16 v[12:15], v[88:91], v[80:83], v[12:15]
	ds_read_b128 v[80:83], v120 offset:6144
	s_waitcnt lgkmcnt(0)
	v_mfma_f32_16x16x32_bf16 v[56:59], v[72:75], v[76:79], v[56:59]
	s_waitcnt vmcnt(0)
	v_mfma_f32_16x16x32_bf16 v[60:63], v[52:55], v[76:79], v[60:63]
	s_waitcnt vmcnt(0) lgkmcnt(0)
	s_barrier
	v_mfma_f32_16x16x32_bf16 v[68:71], v[84:87], v[76:79], v[68:71]
	v_mfma_f32_16x16x32_bf16 v[48:51], v[88:91], v[76:79], v[48:51]
	v_mfma_f32_16x16x32_bf16 v[0:3], v[72:75], v[80:83], v[0:3]
	v_mfma_f32_16x16x32_bf16 v[4:7], v[52:55], v[80:83], v[4:7]
	ds_read_b128 v[52:55], v108 offset:49152
	v_mfma_f32_16x16x32_bf16 v[20:23], v[84:87], v[80:83], v[20:23]
	v_mfma_f32_16x16x32_bf16 v[28:31], v[88:91], v[80:83], v[28:31]
	ds_read_b128 v[72:75], v108 offset:51200
	ds_read_b128 v[76:79], v109 offset:32768
	ds_read_b128 v[80:83], v109 offset:34816
	ds_read_b128 v[84:87], v108 offset:53248
	ds_read_b128 v[88:91], v108 offset:55296
	s_waitcnt lgkmcnt(3)
	v_mfma_f32_16x16x32_bf16 v[16:19], v[52:55], v[76:79], v[16:19]
	v_mfma_f32_16x16x32_bf16 v[24:27], v[72:75], v[76:79], v[24:27]
	s_waitcnt lgkmcnt(1)
	v_mfma_f32_16x16x32_bf16 v[32:35], v[84:87], v[76:79], v[32:35]
	s_waitcnt lgkmcnt(0)
	v_mfma_f32_16x16x32_bf16 v[8:11], v[88:91], v[76:79], v[8:11]
	v_mfma_f32_16x16x32_bf16 v[36:39], v[52:55], v[80:83], v[36:39]
	v_mfma_f32_16x16x32_bf16 v[40:43], v[72:75], v[80:83], v[40:43]
	v_mfma_f32_16x16x32_bf16 v[76:79], v[84:87], v[80:83], v[44:47]
	v_mfma_f32_16x16x32_bf16 v[12:15], v[88:91], v[80:83], v[12:15]
	s_nop 1
	ds_read_b128 v[44:47], v109 offset:36864
	ds_read_b128 v[80:83], v109 offset:38912
	ds_read_b128 v[104:107], v112 offset:49152
	s_waitcnt lgkmcnt(2)
	v_mfma_f32_16x16x32_bf16 v[68:71], v[84:87], v[44:47], v[68:71]
	v_mfma_f32_16x16x32_bf16 v[100:103], v[88:91], v[44:47], v[48:51]
	s_waitcnt lgkmcnt(1)
	v_mfma_f32_16x16x32_bf16 v[0:3], v[52:55], v[80:83], v[0:3]
	v_mfma_f32_16x16x32_bf16 v[4:7], v[72:75], v[80:83], v[4:7]
	v_mfma_f32_16x16x32_bf16 v[84:87], v[84:87], v[80:83], v[20:23]
	v_mfma_f32_16x16x32_bf16 v[80:83], v[88:91], v[80:83], v[28:31]
	ds_read_b128 v[88:91], v112 offset:51200
	s_nop 0
	ds_read_b128 v[20:23], v120 offset:32768
	ds_read_b128 v[28:31], v120 offset:34816
	ds_read_b128 v[108:111], v112 offset:53248
	ds_read_b128 v[112:115], v112 offset:55296
	v_mfma_f32_16x16x32_bf16 v[92:95], v[52:55], v[44:47], v[56:59]
	v_mfma_f32_16x16x32_bf16 v[96:99], v[72:75], v[44:47], v[60:63]
	v_or_b32_e32 v73, s1, v66
	s_addk_i32 s1, 0xc000
	s_lshr_b32 s34, s1, 8
	s_waitcnt lgkmcnt(0)
	v_mfma_f32_16x16x32_bf16 v[48:51], v[112:115], v[20:23], v[8:11]
	s_bfe_u32 s1, s4, 0x90005
	v_lshlrev_b32_e32 v75, 6, v118
	s_cmpk_lt_u32 s2, 0x80
	v_mfma_f32_16x16x32_bf16 v[44:47], v[104:107], v[28:31], v[36:39]
	s_movk_i32 s2, 0xcf
	v_bitop3_b32 v64, v75, s2, v73 bitop3:0xc8
	s_movk_i32 s2, 0xfcf
	v_mfma_f32_16x16x32_bf16 v[36:39], v[108:111], v[28:31], v[76:79]
	ds_read_b128 v[8:11], v120 offset:36864
	s_nop 1
	ds_read_b128 v[76:79], v120 offset:38912
	s_waitcnt vmcnt(0)
	s_waitcnt lgkmcnt(0)
	v_mfma_f32_16x16x32_bf16 v[60:63], v[104:107], v[20:23], v[16:19]
	s_barrier
	s_cselect_b64 vcc, -1, 0
	v_mfma_f32_16x16x32_bf16 v[56:59], v[88:91], v[20:23], v[24:27]
	s_and_b64 s[4:5], vcc, exec
	v_mfma_f32_16x16x32_bf16 v[52:55], v[108:111], v[20:23], v[32:35]
	v_mfma_f32_16x16x32_bf16 v[40:43], v[88:91], v[28:31], v[40:43]
	v_mfma_f32_16x16x32_bf16 v[32:35], v[112:115], v[28:31], v[12:15]
	v_mfma_f32_16x16x32_bf16 v[28:31], v[104:107], v[8:11], v[92:95]
	v_mfma_f32_16x16x32_bf16 v[24:27], v[88:91], v[8:11], v[96:99]
	v_mfma_f32_16x16x32_bf16 v[20:23], v[108:111], v[8:11], v[68:71]
	v_mfma_f32_16x16x32_bf16 v[16:19], v[112:115], v[8:11], v[100:103]
	v_and_b32_e32 v8, 0x80, v116
	v_lshlrev_b32_e32 v8, 2, v8
	v_lshl_or_b32 v8, v73, 3, v8
	global_load_dword v74, v8, s[8:9] offset:4
	global_load_dword v72, v8, s[8:9] offset:132
	global_load_dword v70, v8, s[8:9] offset:260
	global_load_dword v66, v8, s[8:9] offset:388
	v_mfma_f32_16x16x32_bf16 v[12:15], v[104:107], v[76:79], v[0:3]
	v_bitop3_b32 v68, v75, s2, v73 bitop3:0xc8
	v_add_u32_e32 v68, 0x100, v68
	s_cselect_b32 s2, s1, s34
	v_lshlrev_b32_e32 v0, 2, v119
	v_mfma_f32_16x16x32_bf16 v[8:11], v[88:91], v[76:79], v[4:7]
	v_lshl_or_b32 v71, v117, 6, v0
	v_mfma_f32_16x16x32_bf16 v[4:7], v[108:111], v[76:79], v[84:87]
	v_mfma_f32_16x16x32_bf16 v[0:3], v[112:115], v[76:79], v[80:83]
	v_cndmask_b32_e32 v76, v64, v68, vcc
	v_and_b32_e32 v64, 64, v116
	v_cmp_ne_u32_e64 s[4:5], 0, v64
	v_lshlrev_b32_e32 v64, 1, v76
	s_and_saveexec_b64 s[40:41], s[4:5]
	s_xor_b64 s[70:71], exec, s[40:41]
	s_cbranch_execz .LBB0_554
	s_lshl_b32 s34, s2, 8
	s_lshl_b32 s40, s0, 6
	s_or_b32 s34, s34, s40
	v_add_u32_e32 v77, s34, v71
	v_lshl_add_u64 v[68:69], s[14:15], 0, v[64:65]
	s_waitcnt vmcnt(3)
	v_mul_f32_e32 v60, v60, v74
	v_subrev_u32_e32 v78, 64, v77
	v_cvt_pk_bf16_f32 v60, v60, s0
	v_mad_u64_u32 v[78:79], s[40:41], v78, s81, v[68:69]
	global_store_short v[78:79], v60, off
	v_mul_f32_e32 v60, v61, v74
	v_cvt_pk_bf16_f32 v78, v60, s0
	v_subrev_u32_e32 v60, 63, v77
	v_mad_u64_u32 v[60:61], s[40:41], v60, s81, v[68:69]
	global_store_short v[60:61], v78, off
	v_mul_f32_e32 v60, v62, v74
	v_cvt_pk_bf16_f32 v62, v60, s0
	v_subrev_u32_e32 v60, 62, v77
	v_mad_u64_u32 v[60:61], s[40:41], v60, s81, v[68:69]
	global_store_short v[60:61], v62, off
	v_mul_f32_e32 v60, v63, v74
	v_cvt_pk_bf16_f32 v62, v60, s0
	v_subrev_u32_e32 v60, 61, v77
	v_mad_u64_u32 v[60:61], s[40:41], v60, s81, v[68:69]
	global_store_short v[60:61], v62, off
	s_or_saveexec_b64 s[70:71], s[70:71]
	v_lshlrev_b32_e32 v68, 1, v71
	s_xor_b64 exec, exec, s[70:71]
	s_cbranch_execnz .LBB0_555

.LBB0_2008:
	s_and_b64 vcc, exec, s[6:7]
	s_cbranch_vccz .LBB0_2075
	s_add_i32 s6, s84, 0xfe80
	s_waitcnt vmcnt(0)
	v_mov_b32_e32 v116, v164
	s_bfe_u32 s5, s6, 0xe0002
	s_lshl_b32 s4, s5, 7
	v_bfe_u32 v4, v116, 3, 5
	v_xor_b32_e32 v5, v4, v116
	s_and_b32 s2, s84, 3
	v_or_b32_e32 v6, s4, v4
	v_mov_b64_e32 v[0:1], s[20:21]
	v_lshlrev_b32_e32 v5, 4, v5
	v_mad_u64_u32 v[0:1], s[40:41], v6, s81, v[0:1]
	v_and_b32_e32 v64, 0x70, v5
	s_lshl_b32 s7, s2, 15
	v_lshl_add_u64 v[92:93], v[0:1], 0, v[64:65]
	v_lshl_or_b32 v0, v4, 8, s7
	v_mov_b32_e32 v1, v65
	v_and_b32_e32 v3, 0xff, v116
	v_lshl_add_u64 v[0:1], s[30:31], 0, v[0:1]
	v_lshl_add_u64 v[94:95], v[0:1], 0, v[64:65]
	v_lshl_add_u32 v64, v3, 4, s23
	v_add_u32_e32 v3, 0x1000, v64
	v_readfirstlane_b32 s7, v64
	s_mov_b32 m0, s7
	v_readfirstlane_b32 s7, v3
	v_add_u32_e32 v3, 0x2000, v64
	global_load_lds_dwordx4 v[92:93], off
	v_lshl_add_u64 v[0:1], v[92:93], 0, s[38:39]
	s_mov_b32 m0, s7
	v_readfirstlane_b32 s7, v3
	v_add_u32_e32 v3, 0x3000, v64
	global_load_lds_dwordx4 v[0:1], off
	v_lshl_add_u64 v[0:1], v[92:93], 0, s[44:45]
	s_mov_b32 m0, s7
	v_readfirstlane_b32 s7, v3
	global_load_lds_dwordx4 v[0:1], off
	v_lshl_add_u64 v[0:1], v[92:93], 0, s[46:47]
	s_mov_b32 m0, s7
	v_add_u32_e32 v3, 0x5000, v64
	global_load_lds_dwordx4 v[0:1], off
	v_add_u32_e32 v0, 0x4000, v64
	s_mov_b64 s[40:41], 0x2000
	v_readfirstlane_b32 s7, v0
	s_mov_b32 m0, s7
	v_readfirstlane_b32 s7, v3
	v_add_u32_e32 v3, 0x6000, v64
	global_load_lds_dwordx4 v[94:95], off
	v_lshl_add_u64 v[0:1], v[94:95], 0, s[40:41]
	s_mov_b32 m0, s7
	v_readfirstlane_b32 s7, v3
	v_add_u32_e32 v3, 0x7000, v64
	global_load_lds_dwordx4 v[0:1], off
	v_lshl_add_u64 v[0:1], v[94:95], 0, s[48:49]
	s_mov_b32 m0, s7
	s_mov_b64 s[40:41], 0x6000
	v_readfirstlane_b32 s7, v3
	v_lshrrev_b32_e32 v2, 4, v116
	v_and_b32_e32 v66, 15, v116
	global_load_lds_dwordx4 v[0:1], off
	v_lshl_add_u64 v[0:1], v[94:95], 0, s[40:41]
	s_mov_b32 m0, s7
	v_and_b32_e32 v72, 7, v116
	v_bfe_u32 v117, v116, 6, 1
	global_load_lds_dwordx4 v[0:1], off
	v_add_u32_e32 v110, 0x8000, v64
	v_add_u32_e32 v111, 0xf000, v64
	v_add_u32_e32 v113, 0xe000, v64
	v_add_u32_e32 v114, 0xd000, v64
	v_add_u32_e32 v115, 0xc000, v64
	v_add_u32_e32 v121, 0xb000, v64
	v_add_u32_e32 v122, 0xa000, v64
	v_add_u32_e32 v64, 0x9000, v64
	v_readfirstlane_b32 s7, v110
	s_mov_b32 m0, s7
	v_readfirstlane_b32 s7, v64
	v_lshl_add_u64 v[106:107], v[92:93], 0, s[64:65]
	s_mov_b64 s[40:41], 0x6080
	v_lshl_add_u64 v[104:105], v[92:93], 0, s[62:63]
	v_lshl_add_u64 v[96:97], v[94:95], 0, s[40:41]
	s_mov_b64 s[40:41], 0x2080
	v_lshl_add_u64 v[102:103], v[92:93], 0, s[60:61]
	v_lshl_add_u64 v[98:99], v[94:95], 0, s[50:51]
	v_lshl_add_u64 v[100:101], v[94:95], 0, s[40:41]
	v_lshl_add_u64 v[94:95], v[94:95], 0, s[58:59]
	v_lshl_add_u64 v[0:1], v[92:93], 0, s[58:59]
	global_load_lds_dwordx4 v[0:1], off
	s_mov_b32 m0, s7
	v_readfirstlane_b32 s7, v122
	global_load_lds_dwordx4 v[106:107], off
	s_mov_b32 m0, s7
	v_readfirstlane_b32 s7, v121
	global_load_lds_dwordx4 v[104:105], off
	s_mov_b32 m0, s7
	v_readfirstlane_b32 s7, v115
	global_load_lds_dwordx4 v[102:103], off
	s_mov_b32 m0, s7
	v_readfirstlane_b32 s7, v114
	global_load_lds_dwordx4 v[94:95], off
	s_mov_b32 m0, s7
	v_readfirstlane_b32 s7, v113
	global_load_lds_dwordx4 v[100:101], off
	s_mov_b32 m0, s7
	v_readfirstlane_b32 s7, v111
	global_load_lds_dwordx4 v[98:99], off
	s_mov_b32 m0, s7
	s_nop 0
	global_load_lds_dwordx4 v[96:97], off
	v_bitop3_b32 v0, v2, v72, 3 bitop3:0x6c
	v_lshlrev_b32_e32 v5, 7, v66
	v_bfe_u32 v118, v116, 7, 1
	v_lshl_add_u32 v4, v0, 4, s23
	v_lshl_or_b32 v73, v117, 13, v5
	v_add_u32_e32 v108, v4, v73
	v_lshl_or_b32 v76, v118, 13, v5
	s_waitcnt vmcnt(8)
	s_waitcnt vmcnt(8) lgkmcnt(0)
	s_barrier
	ds_read_b128 v[0:3], v108 offset:16384
	v_add_u32_e32 v109, v4, v76
	ds_read_b128 v[4:7], v108 offset:18432
	ds_read_b128 v[8:11], v109
	ds_read_b128 v[12:15], v109 offset:2048
	ds_read_b128 v[20:23], v108 offset:20480
	ds_read_b128 v[28:31], v108 offset:22528
	ds_read_b128 v[48:51], v109 offset:4096
	ds_read_b128 v[52:55], v109 offset:6144
	v_bfe_u32 v119, v116, 4, 2
	v_bitop3_b32 v72, v119, v72, 4 bitop3:0x36
	v_lshl_add_u32 v77, v72, 4, s23
	v_add_u32_e32 v112, v77, v73
	s_waitcnt lgkmcnt(5)
	v_mfma_f32_16x16x32_bf16 v[16:19], v[0:3], v[8:11], 0
	ds_read_b128 v[72:75], v112 offset:16384
	v_add_u32_e32 v120, v77, v76
	v_mfma_f32_16x16x32_bf16 v[24:27], v[4:7], v[8:11], 0
	s_waitcnt lgkmcnt(4)
	v_mfma_f32_16x16x32_bf16 v[32:35], v[20:23], v[8:11], 0
	s_waitcnt lgkmcnt(3)
	v_mfma_f32_16x16x32_bf16 v[8:11], v[28:31], v[8:11], 0
	v_mfma_f32_16x16x32_bf16 v[36:39], v[0:3], v[12:15], 0
	v_mfma_f32_16x16x32_bf16 v[40:43], v[4:7], v[12:15], 0
	v_mfma_f32_16x16x32_bf16 v[44:47], v[20:23], v[12:15], 0
	v_mfma_f32_16x16x32_bf16 v[12:15], v[28:31], v[12:15], 0
	s_lshr_b32 s6, s6, 2
	s_waitcnt lgkmcnt(2)
	v_mfma_f32_16x16x32_bf16 v[56:59], v[0:3], v[48:51], 0
	v_mfma_f32_16x16x32_bf16 v[60:63], v[4:7], v[48:51], 0
	v_mfma_f32_16x16x32_bf16 v[68:71], v[20:23], v[48:51], 0
	v_mfma_f32_16x16x32_bf16 v[48:51], v[28:31], v[48:51], 0
	s_waitcnt lgkmcnt(1)
	v_mfma_f32_16x16x32_bf16 v[0:3], v[0:3], v[52:55], 0
	v_mfma_f32_16x16x32_bf16 v[4:7], v[4:7], v[52:55], 0
	v_mfma_f32_16x16x32_bf16 v[20:23], v[20:23], v[52:55], 0
	v_mfma_f32_16x16x32_bf16 v[28:31], v[28:31], v[52:55], 0
	ds_read_b128 v[52:55], v112 offset:18432
	ds_read_b128 v[76:79], v120
	ds_read_b128 v[80:83], v120 offset:2048
	ds_read_b128 v[84:87], v112 offset:20480
	ds_read_b128 v[88:91], v112 offset:22528
	s_waitcnt lgkmcnt(3)
	v_mfma_f32_16x16x32_bf16 v[16:19], v[72:75], v[76:79], v[16:19]
	v_mfma_f32_16x16x32_bf16 v[24:27], v[52:55], v[76:79], v[24:27]
	s_waitcnt lgkmcnt(1)
	v_mfma_f32_16x16x32_bf16 v[32:35], v[84:87], v[76:79], v[32:35]
	s_waitcnt lgkmcnt(0)
	v_mfma_f32_16x16x32_bf16 v[8:11], v[88:91], v[76:79], v[8:11]
	v_mfma_f32_16x16x32_bf16 v[36:39], v[72:75], v[80:83], v[36:39]
	ds_read_b128 v[76:79], v120 offset:4096
	v_mfma_f32_16x16x32_bf16 v[40:43], v[52:55], v[80:83], v[40:43]
	v_mfma_f32_16x16x32_bf16 v[44:47], v[84:87], v[80:83], v[44:47]
	v_mfma_f32_16x16x32_bf16 v[12:15], v[88:91], v[80:83], v[12:15]
	ds_read_b128 v[80:83], v120 offset:6144
	s_waitcnt lgkmcnt(0)
	v_mfma_f32_16x16x32_bf16 v[56:59], v[72:75], v[76:79], v[56:59]
	s_waitcnt vmcnt(0)
	v_mfma_f32_16x16x32_bf16 v[60:63], v[52:55], v[76:79], v[60:63]
	s_waitcnt vmcnt(0) lgkmcnt(0)
	s_barrier
	v_mfma_f32_16x16x32_bf16 v[68:71], v[84:87], v[76:79], v[68:71]
	v_mfma_f32_16x16x32_bf16 v[48:51], v[88:91], v[76:79], v[48:51]
	v_mfma_f32_16x16x32_bf16 v[0:3], v[72:75], v[80:83], v[0:3]
	v_mfma_f32_16x16x32_bf16 v[4:7], v[52:55], v[80:83], v[4:7]
	ds_read_b128 v[52:55], v108 offset:49152
	v_mfma_f32_16x16x32_bf16 v[20:23], v[84:87], v[80:83], v[20:23]
	v_mfma_f32_16x16x32_bf16 v[28:31], v[88:91], v[80:83], v[28:31]
	ds_read_b128 v[72:75], v108 offset:51200
	ds_read_b128 v[76:79], v109 offset:32768
	ds_read_b128 v[80:83], v109 offset:34816
	ds_read_b128 v[84:87], v108 offset:53248
	ds_read_b128 v[88:91], v108 offset:55296
	s_waitcnt lgkmcnt(3)
	v_mfma_f32_16x16x32_bf16 v[16:19], v[52:55], v[76:79], v[16:19]
	v_mfma_f32_16x16x32_bf16 v[24:27], v[72:75], v[76:79], v[24:27]
	s_waitcnt lgkmcnt(1)
	v_mfma_f32_16x16x32_bf16 v[32:35], v[84:87], v[76:79], v[32:35]
	s_waitcnt lgkmcnt(0)
	v_mfma_f32_16x16x32_bf16 v[8:11], v[88:91], v[76:79], v[8:11]
	v_mfma_f32_16x16x32_bf16 v[36:39], v[52:55], v[80:83], v[36:39]
	v_mfma_f32_16x16x32_bf16 v[40:43], v[72:75], v[80:83], v[40:43]
	v_mfma_f32_16x16x32_bf16 v[76:79], v[84:87], v[80:83], v[44:47]
	v_mfma_f32_16x16x32_bf16 v[12:15], v[88:91], v[80:83], v[12:15]
	s_nop 1
	ds_read_b128 v[44:47], v109 offset:36864
	ds_read_b128 v[80:83], v109 offset:38912
	ds_read_b128 v[104:107], v112 offset:49152
	s_waitcnt lgkmcnt(2)
	v_mfma_f32_16x16x32_bf16 v[68:71], v[84:87], v[44:47], v[68:71]
	v_mfma_f32_16x16x32_bf16 v[100:103], v[88:91], v[44:47], v[48:51]
	s_waitcnt lgkmcnt(1)
	v_mfma_f32_16x16x32_bf16 v[0:3], v[52:55], v[80:83], v[0:3]
	v_mfma_f32_16x16x32_bf16 v[4:7], v[72:75], v[80:83], v[4:7]
	v_mfma_f32_16x16x32_bf16 v[84:87], v[84:87], v[80:83], v[20:23]
	v_mfma_f32_16x16x32_bf16 v[80:83], v[88:91], v[80:83], v[28:31]
	ds_read_b128 v[88:91], v112 offset:51200
	s_nop 0
	ds_read_b128 v[20:23], v120 offset:32768
	ds_read_b128 v[28:31], v120 offset:34816
	ds_read_b128 v[108:111], v112 offset:53248
	ds_read_b128 v[112:115], v112 offset:55296
	v_mfma_f32_16x16x32_bf16 v[92:95], v[52:55], v[44:47], v[56:59]
	v_mfma_f32_16x16x32_bf16 v[96:99], v[72:75], v[44:47], v[60:63]
	v_or_b32_e32 v73, s4, v66
	s_addk_i32 s4, 0xc000
	s_lshr_b32 s36, s4, 8
	s_waitcnt lgkmcnt(0)
	v_mfma_f32_16x16x32_bf16 v[48:51], v[112:115], v[20:23], v[8:11]
	s_bfe_u32 s4, s6, 0x90005
	v_lshlrev_b32_e32 v75, 6, v118
	s_cmpk_lt_u32 s5, 0x80
	v_mfma_f32_16x16x32_bf16 v[44:47], v[104:107], v[28:31], v[36:39]
	s_movk_i32 s5, 0xcf
	v_bitop3_b32 v64, v75, s5, v73 bitop3:0xc8
	s_movk_i32 s5, 0xfcf
	v_mfma_f32_16x16x32_bf16 v[36:39], v[108:111], v[28:31], v[76:79]
	ds_read_b128 v[8:11], v120 offset:36864
	s_nop 1
	ds_read_b128 v[76:79], v120 offset:38912
	s_waitcnt vmcnt(0)
	s_waitcnt lgkmcnt(0)
	v_mfma_f32_16x16x32_bf16 v[60:63], v[104:107], v[20:23], v[16:19]
	s_barrier
	s_cselect_b64 vcc, -1, 0
	v_mfma_f32_16x16x32_bf16 v[56:59], v[88:91], v[20:23], v[24:27]
	s_and_b64 s[6:7], vcc, exec
	v_mfma_f32_16x16x32_bf16 v[52:55], v[108:111], v[20:23], v[32:35]
	v_mfma_f32_16x16x32_bf16 v[40:43], v[88:91], v[28:31], v[40:43]
	v_mfma_f32_16x16x32_bf16 v[32:35], v[112:115], v[28:31], v[12:15]
	v_mfma_f32_16x16x32_bf16 v[28:31], v[104:107], v[8:11], v[92:95]
	v_mfma_f32_16x16x32_bf16 v[24:27], v[88:91], v[8:11], v[96:99]
	v_mfma_f32_16x16x32_bf16 v[20:23], v[108:111], v[8:11], v[68:71]
	v_mfma_f32_16x16x32_bf16 v[16:19], v[112:115], v[8:11], v[100:103]
	v_and_b32_e32 v8, 0x80, v116
	v_lshlrev_b32_e32 v8, 2, v8
	v_lshl_or_b32 v8, v73, 3, v8
	global_load_dword v74, v8, s[10:11] offset:4
	global_load_dword v72, v8, s[10:11] offset:132
	global_load_dword v70, v8, s[10:11] offset:260
	global_load_dword v66, v8, s[10:11] offset:388
	v_mfma_f32_16x16x32_bf16 v[12:15], v[104:107], v[76:79], v[0:3]
	v_bitop3_b32 v68, v75, s5, v73 bitop3:0xc8
	v_add_u32_e32 v68, 0x100, v68
	s_cselect_b32 s5, s4, s36
	v_lshlrev_b32_e32 v0, 2, v119
	v_mfma_f32_16x16x32_bf16 v[8:11], v[88:91], v[76:79], v[4:7]
	v_lshl_or_b32 v71, v117, 6, v0
	v_mfma_f32_16x16x32_bf16 v[4:7], v[108:111], v[76:79], v[84:87]
	v_mfma_f32_16x16x32_bf16 v[0:3], v[112:115], v[76:79], v[80:83]
	v_cndmask_b32_e32 v76, v64, v68, vcc
	v_and_b32_e32 v64, 64, v116
	v_cmp_ne_u32_e64 s[6:7], 0, v64
	v_lshlrev_b32_e32 v64, 1, v76
	s_and_saveexec_b64 s[40:41], s[6:7]
	s_xor_b64 s[70:71], exec, s[40:41]
	s_cbranch_execz .LBB0_2018
	s_lshl_b32 s36, s5, 8
	s_lshl_b32 s40, s2, 6
	s_or_b32 s36, s36, s40
	v_add_u32_e32 v77, s36, v71
	v_lshl_add_u64 v[68:69], s[16:17], 0, v[64:65]
	s_waitcnt vmcnt(3)
	v_mul_f32_e32 v60, v60, v74
	v_subrev_u32_e32 v78, 64, v77
	v_cvt_pk_bf16_f32 v60, v60, s0
	v_mad_u64_u32 v[78:79], s[40:41], v78, s82, v[68:69]
	global_store_short v[78:79], v60, off
	v_mul_f32_e32 v60, v61, v74
	v_cvt_pk_bf16_f32 v78, v60, s0
	v_subrev_u32_e32 v60, 63, v77
	v_mad_u64_u32 v[60:61], s[40:41], v60, s82, v[68:69]
	global_store_short v[60:61], v78, off
	v_mul_f32_e32 v60, v62, v74
	v_cvt_pk_bf16_f32 v62, v60, s0
	v_subrev_u32_e32 v60, 62, v77
	v_mad_u64_u32 v[60:61], s[40:41], v60, s82, v[68:69]
	global_store_short v[60:61], v62, off
	v_mul_f32_e32 v60, v63, v74
	v_cvt_pk_bf16_f32 v62, v60, s0
	v_subrev_u32_e32 v60, 61, v77
	v_mad_u64_u32 v[60:61], s[40:41], v60, s82, v[68:69]
	global_store_short v[60:61], v62, off
	s_or_saveexec_b64 s[70:71], s[70:71]
	v_lshlrev_b32_e32 v68, 1, v71
	s_xor_b64 exec, exec, s[70:71]
	s_cbranch_execnz .LBB0_2019
